# P3 chunk-state scan rewritten: decay factors preloaded per wave, 16-deep window of state loads, counted waits (was store-load-vmcnt0 per chunk)
# speedup vs baseline: 1.0525x; 1.0065x over previous
.LBB0_1888:
	v_lshrrev_b32_e32 v4, 1, v75
	v_ashrrev_i32_e32 v6, 15, v74
	v_bfe_u32 v9, v4, 12, 3
	v_ashrrev_i32_e32 v7, 31, v6
	v_bfe_u32 v8, v75, 1, 15
	v_lshlrev_b64 v[4:5], 25, v[6:7]
	v_lshl_or_b32 v68, v6, 10, v9
	v_lshl_or_b32 v4, v8, 3, v4
	v_or_b32_e32 v6, 0xf8, v68
	v_or_b32_e32 v8, 0xf0, v68
	v_or_b32_e32 v10, 0xe8, v68
	v_or_b32_e32 v12, 0xe0, v68
	v_or_b32_e32 v14, 0xd8, v68
	v_or_b32_e32 v16, 0xd0, v68
	v_or_b32_e32 v18, 0xc8, v68
	v_or_b32_e32 v20, 0xc0, v68
	v_or_b32_e32 v22, 0xb8, v68
	v_or_b32_e32 v24, 0xb0, v68
	v_or_b32_e32 v26, 0xa8, v68
	v_or_b32_e32 v28, 0xa0, v68
	v_or_b32_e32 v30, 0x98, v68
	v_or_b32_e32 v32, 0x90, v68
	v_or_b32_e32 v34, 0x88, v68
	v_or_b32_e32 v36, 0x80, v68
	v_or_b32_e32 v38, 0x78, v68
	v_or_b32_e32 v40, 0x70, v68
	v_or_b32_e32 v42, 0x68, v68
	v_or_b32_e32 v44, 0x60, v68
	v_or_b32_e32 v46, 0x58, v68
	v_or_b32_e32 v48, 0x50, v68
	v_or_b32_e32 v50, 0x48, v68
	v_or_b32_e32 v52, 64, v68
	v_or_b32_e32 v54, 56, v68
	v_or_b32_e32 v56, 48, v68
	v_or_b32_e32 v58, 40, v68
	v_or_b32_e32 v60, 32, v68
	v_or_b32_e32 v62, 24, v68
	v_or_b32_e32 v64, 16, v68
	v_or_b32_e32 v66, 8, v68
	v_ashrrev_i32_e32 v7, 31, v6
	v_ashrrev_i32_e32 v9, 31, v8
	v_ashrrev_i32_e32 v11, 31, v10
	v_ashrrev_i32_e32 v13, 31, v12
	v_ashrrev_i32_e32 v15, 31, v14
	v_ashrrev_i32_e32 v17, 31, v16
	v_ashrrev_i32_e32 v19, 31, v18
	v_ashrrev_i32_e32 v21, 31, v20
	v_ashrrev_i32_e32 v23, 31, v22
	v_ashrrev_i32_e32 v25, 31, v24
	v_ashrrev_i32_e32 v27, 31, v26
	v_ashrrev_i32_e32 v29, 31, v28
	v_ashrrev_i32_e32 v31, 31, v30
	v_ashrrev_i32_e32 v33, 31, v32
	v_ashrrev_i32_e32 v35, 31, v34
	v_ashrrev_i32_e32 v37, 31, v36
	v_ashrrev_i32_e32 v39, 31, v38
	v_ashrrev_i32_e32 v41, 31, v40
	v_ashrrev_i32_e32 v43, 31, v42
	v_ashrrev_i32_e32 v45, 31, v44
	v_ashrrev_i32_e32 v47, 31, v46
	v_ashrrev_i32_e32 v49, 31, v48
	v_ashrrev_i32_e32 v51, 31, v50
	v_ashrrev_i32_e32 v53, 31, v52
	v_ashrrev_i32_e32 v55, 31, v54
	v_ashrrev_i32_e32 v57, 31, v56
	v_ashrrev_i32_e32 v59, 31, v58
	v_ashrrev_i32_e32 v61, 31, v60
	v_ashrrev_i32_e32 v63, 31, v62
	v_ashrrev_i32_e32 v65, 31, v64
	v_ashrrev_i32_e32 v67, 31, v66
	v_ashrrev_i32_e32 v69, 31, v68
	v_mov_b32_e32 v72, 0
	v_lshl_add_u64 v[4:5], s[88:89], 0, v[4:5]
	v_lshl_add_u64 v[6:7], v[6:7], 2, v[2:3]
	v_lshl_add_u64 v[8:9], v[8:9], 2, v[2:3]
	v_lshl_add_u64 v[10:11], v[10:11], 2, v[2:3]
	v_lshl_add_u64 v[12:13], v[12:13], 2, v[2:3]
	v_lshl_add_u64 v[14:15], v[14:15], 2, v[2:3]
	v_lshl_add_u64 v[16:17], v[16:17], 2, v[2:3]
	v_lshl_add_u64 v[18:19], v[18:19], 2, v[2:3]
	v_lshl_add_u64 v[20:21], v[20:21], 2, v[2:3]
	v_lshl_add_u64 v[22:23], v[22:23], 2, v[2:3]
	v_lshl_add_u64 v[24:25], v[24:25], 2, v[2:3]
	v_lshl_add_u64 v[26:27], v[26:27], 2, v[2:3]
	v_lshl_add_u64 v[28:29], v[28:29], 2, v[2:3]
	v_lshl_add_u64 v[30:31], v[30:31], 2, v[2:3]
	v_lshl_add_u64 v[32:33], v[32:33], 2, v[2:3]
	v_lshl_add_u64 v[34:35], v[34:35], 2, v[2:3]
	v_lshl_add_u64 v[36:37], v[36:37], 2, v[2:3]
	v_lshl_add_u64 v[38:39], v[38:39], 2, v[2:3]
	v_lshl_add_u64 v[40:41], v[40:41], 2, v[2:3]
	v_lshl_add_u64 v[42:43], v[42:43], 2, v[2:3]
	v_lshl_add_u64 v[44:45], v[44:45], 2, v[2:3]
	v_lshl_add_u64 v[46:47], v[46:47], 2, v[2:3]
	v_lshl_add_u64 v[48:49], v[48:49], 2, v[2:3]
	v_lshl_add_u64 v[50:51], v[50:51], 2, v[2:3]
	v_lshl_add_u64 v[52:53], v[52:53], 2, v[2:3]
	v_lshl_add_u64 v[54:55], v[54:55], 2, v[2:3]
	v_lshl_add_u64 v[56:57], v[56:57], 2, v[2:3]
	v_lshl_add_u64 v[58:59], v[58:59], 2, v[2:3]
	v_lshl_add_u64 v[60:61], v[60:61], 2, v[2:3]
	v_lshl_add_u64 v[62:63], v[62:63], 2, v[2:3]
	v_lshl_add_u64 v[64:65], v[64:65], 2, v[2:3]
	v_lshl_add_u64 v[66:67], v[66:67], 2, v[2:3]
	v_lshl_add_u64 v[68:69], v[68:69], 2, v[2:3]
	s_mov_b64 s[10:11], s[90:91]
	s_mov_b64 s[12:13], 0
	v_mov_b32_e32 v73, v72
	v_and_b32_e32 v6, 63, v0
	v_lshlrev_b32_e32 v6, 5, v6
	v_mov_b32_e32 v7, 0
	v_lshl_add_u64 v[6:7], v[68:69], 0, v[6:7]
	v_lshl_add_u64 v[6:7], s[90:91], 0, v[6:7]
	global_load_dword v8, v[6:7], off
	global_load_dword v9, v[6:7], off offset:2048
	s_mov_b64 s[12:13], 0x400000
	v_lshl_add_u64 v[44:45], v[4:5], 0, s[12:13]
	s_mov_b64 s[12:13], 0
	global_load_dwordx2 v[10:11], v[4:5], off
	s_add_u32 s12, s12, 0x40000
	s_addc_u32 s13, s13, 0
	v_lshl_add_u64 v[42:43], v[4:5], 0, s[12:13]
	global_load_dwordx2 v[12:13], v[42:43], off
	s_add_u32 s12, s12, 0x40000
	s_addc_u32 s13, s13, 0
	v_lshl_add_u64 v[42:43], v[4:5], 0, s[12:13]
	global_load_dwordx2 v[14:15], v[42:43], off
	s_add_u32 s12, s12, 0x40000
	s_addc_u32 s13, s13, 0
	v_lshl_add_u64 v[42:43], v[4:5], 0, s[12:13]
	global_load_dwordx2 v[16:17], v[42:43], off
	s_add_u32 s12, s12, 0x40000
	s_addc_u32 s13, s13, 0
	v_lshl_add_u64 v[42:43], v[4:5], 0, s[12:13]
	global_load_dwordx2 v[18:19], v[42:43], off
	s_add_u32 s12, s12, 0x40000
	s_addc_u32 s13, s13, 0
	v_lshl_add_u64 v[42:43], v[4:5], 0, s[12:13]
	global_load_dwordx2 v[20:21], v[42:43], off
	s_add_u32 s12, s12, 0x40000
	s_addc_u32 s13, s13, 0
	v_lshl_add_u64 v[42:43], v[4:5], 0, s[12:13]
	global_load_dwordx2 v[22:23], v[42:43], off
	s_add_u32 s12, s12, 0x40000
	s_addc_u32 s13, s13, 0
	v_lshl_add_u64 v[42:43], v[4:5], 0, s[12:13]
	global_load_dwordx2 v[24:25], v[42:43], off
	s_add_u32 s12, s12, 0x40000
	s_addc_u32 s13, s13, 0
	v_lshl_add_u64 v[42:43], v[4:5], 0, s[12:13]
	global_load_dwordx2 v[26:27], v[42:43], off
	s_add_u32 s12, s12, 0x40000
	s_addc_u32 s13, s13, 0
	v_lshl_add_u64 v[42:43], v[4:5], 0, s[12:13]
	global_load_dwordx2 v[28:29], v[42:43], off
	s_add_u32 s12, s12, 0x40000
	s_addc_u32 s13, s13, 0
	v_lshl_add_u64 v[42:43], v[4:5], 0, s[12:13]
	global_load_dwordx2 v[30:31], v[42:43], off
	s_add_u32 s12, s12, 0x40000
	s_addc_u32 s13, s13, 0
	v_lshl_add_u64 v[42:43], v[4:5], 0, s[12:13]
	global_load_dwordx2 v[32:33], v[42:43], off
	s_add_u32 s12, s12, 0x40000
	s_addc_u32 s13, s13, 0
	v_lshl_add_u64 v[42:43], v[4:5], 0, s[12:13]
	global_load_dwordx2 v[34:35], v[42:43], off
	s_add_u32 s12, s12, 0x40000
	s_addc_u32 s13, s13, 0
	v_lshl_add_u64 v[42:43], v[4:5], 0, s[12:13]
	global_load_dwordx2 v[36:37], v[42:43], off
	s_add_u32 s12, s12, 0x40000
	s_addc_u32 s13, s13, 0
	v_lshl_add_u64 v[42:43], v[4:5], 0, s[12:13]
	global_load_dwordx2 v[38:39], v[42:43], off
	s_add_u32 s12, s12, 0x40000
	s_addc_u32 s13, s13, 0
	v_lshl_add_u64 v[42:43], v[4:5], 0, s[12:13]
	global_load_dwordx2 v[40:41], v[42:43], off
	s_add_u32 s12, s12, 0x40000
	s_addc_u32 s13, s13, 0
	s_mov_b64 s[12:13], 0
	s_waitcnt vmcnt(15)
	v_readlane_b32 s10, v8, 0
	v_lshl_add_u64 v[42:43], v[4:5], 0, s[12:13]
	global_store_dwordx2 v[42:43], v[72:73], off
	v_lshl_add_u64 v[46:47], v[44:45], 0, s[12:13]
	v_fma_f32 v72, v72, s10, v10
	v_fma_f32 v73, v73, s10, v11
	global_load_dwordx2 v[10:11], v[46:47], off
	s_add_u32 s12, s12, 0x40000
	s_addc_u32 s13, s13, 0
	s_waitcnt vmcnt(16)
	v_readlane_b32 s10, v8, 1
	v_lshl_add_u64 v[42:43], v[4:5], 0, s[12:13]
	global_store_dwordx2 v[42:43], v[72:73], off
	v_lshl_add_u64 v[46:47], v[44:45], 0, s[12:13]
	v_fma_f32 v72, v72, s10, v12
	v_fma_f32 v73, v73, s10, v13
	global_load_dwordx2 v[12:13], v[46:47], off
	s_add_u32 s12, s12, 0x40000
	s_addc_u32 s13, s13, 0
	s_waitcnt vmcnt(17)
	v_readlane_b32 s10, v8, 2
	v_lshl_add_u64 v[42:43], v[4:5], 0, s[12:13]
	global_store_dwordx2 v[42:43], v[72:73], off
	v_lshl_add_u64 v[46:47], v[44:45], 0, s[12:13]
	v_fma_f32 v72, v72, s10, v14
	v_fma_f32 v73, v73, s10, v15
	global_load_dwordx2 v[14:15], v[46:47], off
	s_add_u32 s12, s12, 0x40000
	s_addc_u32 s13, s13, 0
	s_waitcnt vmcnt(18)
	v_readlane_b32 s10, v8, 3
	v_lshl_add_u64 v[42:43], v[4:5], 0, s[12:13]
	global_store_dwordx2 v[42:43], v[72:73], off
	v_lshl_add_u64 v[46:47], v[44:45], 0, s[12:13]
	v_fma_f32 v72, v72, s10, v16
	v_fma_f32 v73, v73, s10, v17
	global_load_dwordx2 v[16:17], v[46:47], off
	s_add_u32 s12, s12, 0x40000
	s_addc_u32 s13, s13, 0
	s_waitcnt vmcnt(19)
	v_readlane_b32 s10, v8, 4
	v_lshl_add_u64 v[42:43], v[4:5], 0, s[12:13]
	global_store_dwordx2 v[42:43], v[72:73], off
	v_lshl_add_u64 v[46:47], v[44:45], 0, s[12:13]
	v_fma_f32 v72, v72, s10, v18
	v_fma_f32 v73, v73, s10, v19
	global_load_dwordx2 v[18:19], v[46:47], off
	s_add_u32 s12, s12, 0x40000
	s_addc_u32 s13, s13, 0
	s_waitcnt vmcnt(20)
	v_readlane_b32 s10, v8, 5
	v_lshl_add_u64 v[42:43], v[4:5], 0, s[12:13]
	global_store_dwordx2 v[42:43], v[72:73], off
	v_lshl_add_u64 v[46:47], v[44:45], 0, s[12:13]
	v_fma_f32 v72, v72, s10, v20
	v_fma_f32 v73, v73, s10, v21
	global_load_dwordx2 v[20:21], v[46:47], off
	s_add_u32 s12, s12, 0x40000
	s_addc_u32 s13, s13, 0
	s_waitcnt vmcnt(21)
	v_readlane_b32 s10, v8, 6
	v_lshl_add_u64 v[42:43], v[4:5], 0, s[12:13]
	global_store_dwordx2 v[42:43], v[72:73], off
	v_lshl_add_u64 v[46:47], v[44:45], 0, s[12:13]
	v_fma_f32 v72, v72, s10, v22
	v_fma_f32 v73, v73, s10, v23
	global_load_dwordx2 v[22:23], v[46:47], off
	s_add_u32 s12, s12, 0x40000
	s_addc_u32 s13, s13, 0
	s_waitcnt vmcnt(22)
	v_readlane_b32 s10, v8, 7
	v_lshl_add_u64 v[42:43], v[4:5], 0, s[12:13]
	global_store_dwordx2 v[42:43], v[72:73], off
	v_lshl_add_u64 v[46:47], v[44:45], 0, s[12:13]
	v_fma_f32 v72, v72, s10, v24
	v_fma_f32 v73, v73, s10, v25
	global_load_dwordx2 v[24:25], v[46:47], off
	s_add_u32 s12, s12, 0x40000
	s_addc_u32 s13, s13, 0
	s_waitcnt vmcnt(23)
	v_readlane_b32 s10, v8, 8
	v_lshl_add_u64 v[42:43], v[4:5], 0, s[12:13]
	global_store_dwordx2 v[42:43], v[72:73], off
	v_lshl_add_u64 v[46:47], v[44:45], 0, s[12:13]
	v_fma_f32 v72, v72, s10, v26
	v_fma_f32 v73, v73, s10, v27
	global_load_dwordx2 v[26:27], v[46:47], off
	s_add_u32 s12, s12, 0x40000
	s_addc_u32 s13, s13, 0
	s_waitcnt vmcnt(24)
	v_readlane_b32 s10, v8, 9
	v_lshl_add_u64 v[42:43], v[4:5], 0, s[12:13]
	global_store_dwordx2 v[42:43], v[72:73], off
	v_lshl_add_u64 v[46:47], v[44:45], 0, s[12:13]
	v_fma_f32 v72, v72, s10, v28
	v_fma_f32 v73, v73, s10, v29
	global_load_dwordx2 v[28:29], v[46:47], off
	s_add_u32 s12, s12, 0x40000
	s_addc_u32 s13, s13, 0
	s_waitcnt vmcnt(25)
	v_readlane_b32 s10, v8, 10
	v_lshl_add_u64 v[42:43], v[4:5], 0, s[12:13]
	global_store_dwordx2 v[42:43], v[72:73], off
	v_lshl_add_u64 v[46:47], v[44:45], 0, s[12:13]
	v_fma_f32 v72, v72, s10, v30
	v_fma_f32 v73, v73, s10, v31
	global_load_dwordx2 v[30:31], v[46:47], off
	s_add_u32 s12, s12, 0x40000
	s_addc_u32 s13, s13, 0
	s_waitcnt vmcnt(26)
	v_readlane_b32 s10, v8, 11
	v_lshl_add_u64 v[42:43], v[4:5], 0, s[12:13]
	global_store_dwordx2 v[42:43], v[72:73], off
	v_lshl_add_u64 v[46:47], v[44:45], 0, s[12:13]
	v_fma_f32 v72, v72, s10, v32
	v_fma_f32 v73, v73, s10, v33
	global_load_dwordx2 v[32:33], v[46:47], off
	s_add_u32 s12, s12, 0x40000
	s_addc_u32 s13, s13, 0
	s_waitcnt vmcnt(27)
	v_readlane_b32 s10, v8, 12
	v_lshl_add_u64 v[42:43], v[4:5], 0, s[12:13]
	global_store_dwordx2 v[42:43], v[72:73], off
	v_lshl_add_u64 v[46:47], v[44:45], 0, s[12:13]
	v_fma_f32 v72, v72, s10, v34
	v_fma_f32 v73, v73, s10, v35
	global_load_dwordx2 v[34:35], v[46:47], off
	s_add_u32 s12, s12, 0x40000
	s_addc_u32 s13, s13, 0
	s_waitcnt vmcnt(28)
	v_readlane_b32 s10, v8, 13
	v_lshl_add_u64 v[42:43], v[4:5], 0, s[12:13]
	global_store_dwordx2 v[42:43], v[72:73], off
	v_lshl_add_u64 v[46:47], v[44:45], 0, s[12:13]
	v_fma_f32 v72, v72, s10, v36
	v_fma_f32 v73, v73, s10, v37
	global_load_dwordx2 v[36:37], v[46:47], off
	s_add_u32 s12, s12, 0x40000
	s_addc_u32 s13, s13, 0
	s_waitcnt vmcnt(29)
	v_readlane_b32 s10, v8, 14
	v_lshl_add_u64 v[42:43], v[4:5], 0, s[12:13]
	global_store_dwordx2 v[42:43], v[72:73], off
	v_lshl_add_u64 v[46:47], v[44:45], 0, s[12:13]
	v_fma_f32 v72, v72, s10, v38
	v_fma_f32 v73, v73, s10, v39
	global_load_dwordx2 v[38:39], v[46:47], off
	s_add_u32 s12, s12, 0x40000
	s_addc_u32 s13, s13, 0
	s_waitcnt vmcnt(30)
	v_readlane_b32 s10, v8, 15
	v_lshl_add_u64 v[42:43], v[4:5], 0, s[12:13]
	global_store_dwordx2 v[42:43], v[72:73], off
	v_lshl_add_u64 v[46:47], v[44:45], 0, s[12:13]
	v_fma_f32 v72, v72, s10, v40
	v_fma_f32 v73, v73, s10, v41
	global_load_dwordx2 v[40:41], v[46:47], off
	s_add_u32 s12, s12, 0x40000
	s_addc_u32 s13, s13, 0
	s_waitcnt vmcnt(30)
	v_readlane_b32 s10, v8, 16
	v_lshl_add_u64 v[42:43], v[4:5], 0, s[12:13]
	global_store_dwordx2 v[42:43], v[72:73], off
	v_lshl_add_u64 v[46:47], v[44:45], 0, s[12:13]
	v_fma_f32 v72, v72, s10, v10
	v_fma_f32 v73, v73, s10, v11
	global_load_dwordx2 v[10:11], v[46:47], off
	s_add_u32 s12, s12, 0x40000
	s_addc_u32 s13, s13, 0
	s_waitcnt vmcnt(30)
	v_readlane_b32 s10, v8, 17
	v_lshl_add_u64 v[42:43], v[4:5], 0, s[12:13]
	global_store_dwordx2 v[42:43], v[72:73], off
	v_lshl_add_u64 v[46:47], v[44:45], 0, s[12:13]
	v_fma_f32 v72, v72, s10, v12
	v_fma_f32 v73, v73, s10, v13
	global_load_dwordx2 v[12:13], v[46:47], off
	s_add_u32 s12, s12, 0x40000
	s_addc_u32 s13, s13, 0
	s_waitcnt vmcnt(30)
	v_readlane_b32 s10, v8, 18
	v_lshl_add_u64 v[42:43], v[4:5], 0, s[12:13]
	global_store_dwordx2 v[42:43], v[72:73], off
	v_lshl_add_u64 v[46:47], v[44:45], 0, s[12:13]
	v_fma_f32 v72, v72, s10, v14
	v_fma_f32 v73, v73, s10, v15
	global_load_dwordx2 v[14:15], v[46:47], off
	s_add_u32 s12, s12, 0x40000
	s_addc_u32 s13, s13, 0
	s_waitcnt vmcnt(30)
	v_readlane_b32 s10, v8, 19
	v_lshl_add_u64 v[42:43], v[4:5], 0, s[12:13]
	global_store_dwordx2 v[42:43], v[72:73], off
	v_lshl_add_u64 v[46:47], v[44:45], 0, s[12:13]
	v_fma_f32 v72, v72, s10, v16
	v_fma_f32 v73, v73, s10, v17
	global_load_dwordx2 v[16:17], v[46:47], off
	s_add_u32 s12, s12, 0x40000
	s_addc_u32 s13, s13, 0
	s_waitcnt vmcnt(30)
	v_readlane_b32 s10, v8, 20
	v_lshl_add_u64 v[42:43], v[4:5], 0, s[12:13]
	global_store_dwordx2 v[42:43], v[72:73], off
	v_lshl_add_u64 v[46:47], v[44:45], 0, s[12:13]
	v_fma_f32 v72, v72, s10, v18
	v_fma_f32 v73, v73, s10, v19
	global_load_dwordx2 v[18:19], v[46:47], off
	s_add_u32 s12, s12, 0x40000
	s_addc_u32 s13, s13, 0
	s_waitcnt vmcnt(30)
	v_readlane_b32 s10, v8, 21
	v_lshl_add_u64 v[42:43], v[4:5], 0, s[12:13]
	global_store_dwordx2 v[42:43], v[72:73], off
	v_lshl_add_u64 v[46:47], v[44:45], 0, s[12:13]
	v_fma_f32 v72, v72, s10, v20
	v_fma_f32 v73, v73, s10, v21
	global_load_dwordx2 v[20:21], v[46:47], off
	s_add_u32 s12, s12, 0x40000
	s_addc_u32 s13, s13, 0
	s_waitcnt vmcnt(30)
	v_readlane_b32 s10, v8, 22
	v_lshl_add_u64 v[42:43], v[4:5], 0, s[12:13]
	global_store_dwordx2 v[42:43], v[72:73], off
	v_lshl_add_u64 v[46:47], v[44:45], 0, s[12:13]
	v_fma_f32 v72, v72, s10, v22
	v_fma_f32 v73, v73, s10, v23
	global_load_dwordx2 v[22:23], v[46:47], off
	s_add_u32 s12, s12, 0x40000
	s_addc_u32 s13, s13, 0
	s_waitcnt vmcnt(30)
	v_readlane_b32 s10, v8, 23
	v_lshl_add_u64 v[42:43], v[4:5], 0, s[12:13]
	global_store_dwordx2 v[42:43], v[72:73], off
	v_lshl_add_u64 v[46:47], v[44:45], 0, s[12:13]
	v_fma_f32 v72, v72, s10, v24
	v_fma_f32 v73, v73, s10, v25
	global_load_dwordx2 v[24:25], v[46:47], off
	s_add_u32 s12, s12, 0x40000
	s_addc_u32 s13, s13, 0
	s_waitcnt vmcnt(30)
	v_readlane_b32 s10, v8, 24
	v_lshl_add_u64 v[42:43], v[4:5], 0, s[12:13]
	global_store_dwordx2 v[42:43], v[72:73], off
	v_lshl_add_u64 v[46:47], v[44:45], 0, s[12:13]
	v_fma_f32 v72, v72, s10, v26
	v_fma_f32 v73, v73, s10, v27
	global_load_dwordx2 v[26:27], v[46:47], off
	s_add_u32 s12, s12, 0x40000
	s_addc_u32 s13, s13, 0
	s_waitcnt vmcnt(30)
	v_readlane_b32 s10, v8, 25
	v_lshl_add_u64 v[42:43], v[4:5], 0, s[12:13]
	global_store_dwordx2 v[42:43], v[72:73], off
	v_lshl_add_u64 v[46:47], v[44:45], 0, s[12:13]
	v_fma_f32 v72, v72, s10, v28
	v_fma_f32 v73, v73, s10, v29
	global_load_dwordx2 v[28:29], v[46:47], off
	s_add_u32 s12, s12, 0x40000
	s_addc_u32 s13, s13, 0
	s_waitcnt vmcnt(30)
	v_readlane_b32 s10, v8, 26
	v_lshl_add_u64 v[42:43], v[4:5], 0, s[12:13]
	global_store_dwordx2 v[42:43], v[72:73], off
	v_lshl_add_u64 v[46:47], v[44:45], 0, s[12:13]
	v_fma_f32 v72, v72, s10, v30
	v_fma_f32 v73, v73, s10, v31
	global_load_dwordx2 v[30:31], v[46:47], off
	s_add_u32 s12, s12, 0x40000
	s_addc_u32 s13, s13, 0
	s_waitcnt vmcnt(30)
	v_readlane_b32 s10, v8, 27
	v_lshl_add_u64 v[42:43], v[4:5], 0, s[12:13]
	global_store_dwordx2 v[42:43], v[72:73], off
	v_lshl_add_u64 v[46:47], v[44:45], 0, s[12:13]
	v_fma_f32 v72, v72, s10, v32
	v_fma_f32 v73, v73, s10, v33
	global_load_dwordx2 v[32:33], v[46:47], off
	s_add_u32 s12, s12, 0x40000
	s_addc_u32 s13, s13, 0
	s_waitcnt vmcnt(30)
	v_readlane_b32 s10, v8, 28
	v_lshl_add_u64 v[42:43], v[4:5], 0, s[12:13]
	global_store_dwordx2 v[42:43], v[72:73], off
	v_lshl_add_u64 v[46:47], v[44:45], 0, s[12:13]
	v_fma_f32 v72, v72, s10, v34
	v_fma_f32 v73, v73, s10, v35
	global_load_dwordx2 v[34:35], v[46:47], off
	s_add_u32 s12, s12, 0x40000
	s_addc_u32 s13, s13, 0
	s_waitcnt vmcnt(30)
	v_readlane_b32 s10, v8, 29
	v_lshl_add_u64 v[42:43], v[4:5], 0, s[12:13]
	global_store_dwordx2 v[42:43], v[72:73], off
	v_lshl_add_u64 v[46:47], v[44:45], 0, s[12:13]
	v_fma_f32 v72, v72, s10, v36
	v_fma_f32 v73, v73, s10, v37
	global_load_dwordx2 v[36:37], v[46:47], off
	s_add_u32 s12, s12, 0x40000
	s_addc_u32 s13, s13, 0
	s_waitcnt vmcnt(30)
	v_readlane_b32 s10, v8, 30
	v_lshl_add_u64 v[42:43], v[4:5], 0, s[12:13]
	global_store_dwordx2 v[42:43], v[72:73], off
	v_lshl_add_u64 v[46:47], v[44:45], 0, s[12:13]
	v_fma_f32 v72, v72, s10, v38
	v_fma_f32 v73, v73, s10, v39
	global_load_dwordx2 v[38:39], v[46:47], off
	s_add_u32 s12, s12, 0x40000
	s_addc_u32 s13, s13, 0
	s_waitcnt vmcnt(30)
	v_readlane_b32 s10, v8, 31
	v_lshl_add_u64 v[42:43], v[4:5], 0, s[12:13]
	global_store_dwordx2 v[42:43], v[72:73], off
	v_lshl_add_u64 v[46:47], v[44:45], 0, s[12:13]
	v_fma_f32 v72, v72, s10, v40
	v_fma_f32 v73, v73, s10, v41
	global_load_dwordx2 v[40:41], v[46:47], off
	s_add_u32 s12, s12, 0x40000
	s_addc_u32 s13, s13, 0
	s_waitcnt vmcnt(30)
	v_readlane_b32 s10, v8, 32
	v_lshl_add_u64 v[42:43], v[4:5], 0, s[12:13]
	global_store_dwordx2 v[42:43], v[72:73], off
	v_lshl_add_u64 v[46:47], v[44:45], 0, s[12:13]
	v_fma_f32 v72, v72, s10, v10
	v_fma_f32 v73, v73, s10, v11
	global_load_dwordx2 v[10:11], v[46:47], off
	s_add_u32 s12, s12, 0x40000
	s_addc_u32 s13, s13, 0
	s_waitcnt vmcnt(30)
	v_readlane_b32 s10, v8, 33
	v_lshl_add_u64 v[42:43], v[4:5], 0, s[12:13]
	global_store_dwordx2 v[42:43], v[72:73], off
	v_lshl_add_u64 v[46:47], v[44:45], 0, s[12:13]
	v_fma_f32 v72, v72, s10, v12
	v_fma_f32 v73, v73, s10, v13
	global_load_dwordx2 v[12:13], v[46:47], off
	s_add_u32 s12, s12, 0x40000
	s_addc_u32 s13, s13, 0
	s_waitcnt vmcnt(30)
	v_readlane_b32 s10, v8, 34
	v_lshl_add_u64 v[42:43], v[4:5], 0, s[12:13]
	global_store_dwordx2 v[42:43], v[72:73], off
	v_lshl_add_u64 v[46:47], v[44:45], 0, s[12:13]
	v_fma_f32 v72, v72, s10, v14
	v_fma_f32 v73, v73, s10, v15
	global_load_dwordx2 v[14:15], v[46:47], off
	s_add_u32 s12, s12, 0x40000
	s_addc_u32 s13, s13, 0
	s_waitcnt vmcnt(30)
	v_readlane_b32 s10, v8, 35
	v_lshl_add_u64 v[42:43], v[4:5], 0, s[12:13]
	global_store_dwordx2 v[42:43], v[72:73], off
	v_lshl_add_u64 v[46:47], v[44:45], 0, s[12:13]
	v_fma_f32 v72, v72, s10, v16
	v_fma_f32 v73, v73, s10, v17
	global_load_dwordx2 v[16:17], v[46:47], off
	s_add_u32 s12, s12, 0x40000
	s_addc_u32 s13, s13, 0
	s_waitcnt vmcnt(30)
	v_readlane_b32 s10, v8, 36
	v_lshl_add_u64 v[42:43], v[4:5], 0, s[12:13]
	global_store_dwordx2 v[42:43], v[72:73], off
	v_lshl_add_u64 v[46:47], v[44:45], 0, s[12:13]
	v_fma_f32 v72, v72, s10, v18
	v_fma_f32 v73, v73, s10, v19
	global_load_dwordx2 v[18:19], v[46:47], off
	s_add_u32 s12, s12, 0x40000
	s_addc_u32 s13, s13, 0
	s_waitcnt vmcnt(30)
	v_readlane_b32 s10, v8, 37
	v_lshl_add_u64 v[42:43], v[4:5], 0, s[12:13]
	global_store_dwordx2 v[42:43], v[72:73], off
	v_lshl_add_u64 v[46:47], v[44:45], 0, s[12:13]
	v_fma_f32 v72, v72, s10, v20
	v_fma_f32 v73, v73, s10, v21
	global_load_dwordx2 v[20:21], v[46:47], off
	s_add_u32 s12, s12, 0x40000
	s_addc_u32 s13, s13, 0
	s_waitcnt vmcnt(30)
	v_readlane_b32 s10, v8, 38
	v_lshl_add_u64 v[42:43], v[4:5], 0, s[12:13]
	global_store_dwordx2 v[42:43], v[72:73], off
	v_lshl_add_u64 v[46:47], v[44:45], 0, s[12:13]
	v_fma_f32 v72, v72, s10, v22
	v_fma_f32 v73, v73, s10, v23
	global_load_dwordx2 v[22:23], v[46:47], off
	s_add_u32 s12, s12, 0x40000
	s_addc_u32 s13, s13, 0
	s_waitcnt vmcnt(30)
	v_readlane_b32 s10, v8, 39
	v_lshl_add_u64 v[42:43], v[4:5], 0, s[12:13]
	global_store_dwordx2 v[42:43], v[72:73], off
	v_lshl_add_u64 v[46:47], v[44:45], 0, s[12:13]
	v_fma_f32 v72, v72, s10, v24
	v_fma_f32 v73, v73, s10, v25
	global_load_dwordx2 v[24:25], v[46:47], off
	s_add_u32 s12, s12, 0x40000
	s_addc_u32 s13, s13, 0
	s_waitcnt vmcnt(30)
	v_readlane_b32 s10, v8, 40
	v_lshl_add_u64 v[42:43], v[4:5], 0, s[12:13]
	global_store_dwordx2 v[42:43], v[72:73], off
	v_lshl_add_u64 v[46:47], v[44:45], 0, s[12:13]
	v_fma_f32 v72, v72, s10, v26
	v_fma_f32 v73, v73, s10, v27
	global_load_dwordx2 v[26:27], v[46:47], off
	s_add_u32 s12, s12, 0x40000
	s_addc_u32 s13, s13, 0
	s_waitcnt vmcnt(30)
	v_readlane_b32 s10, v8, 41
	v_lshl_add_u64 v[42:43], v[4:5], 0, s[12:13]
	global_store_dwordx2 v[42:43], v[72:73], off
	v_lshl_add_u64 v[46:47], v[44:45], 0, s[12:13]
	v_fma_f32 v72, v72, s10, v28
	v_fma_f32 v73, v73, s10, v29
	global_load_dwordx2 v[28:29], v[46:47], off
	s_add_u32 s12, s12, 0x40000
	s_addc_u32 s13, s13, 0
	s_waitcnt vmcnt(30)
	v_readlane_b32 s10, v8, 42
	v_lshl_add_u64 v[42:43], v[4:5], 0, s[12:13]
	global_store_dwordx2 v[42:43], v[72:73], off
	v_lshl_add_u64 v[46:47], v[44:45], 0, s[12:13]
	v_fma_f32 v72, v72, s10, v30
	v_fma_f32 v73, v73, s10, v31
	global_load_dwordx2 v[30:31], v[46:47], off
	s_add_u32 s12, s12, 0x40000
	s_addc_u32 s13, s13, 0
	s_waitcnt vmcnt(30)
	v_readlane_b32 s10, v8, 43
	v_lshl_add_u64 v[42:43], v[4:5], 0, s[12:13]
	global_store_dwordx2 v[42:43], v[72:73], off
	v_lshl_add_u64 v[46:47], v[44:45], 0, s[12:13]
	v_fma_f32 v72, v72, s10, v32
	v_fma_f32 v73, v73, s10, v33
	global_load_dwordx2 v[32:33], v[46:47], off
	s_add_u32 s12, s12, 0x40000
	s_addc_u32 s13, s13, 0
	s_waitcnt vmcnt(30)
	v_readlane_b32 s10, v8, 44
	v_lshl_add_u64 v[42:43], v[4:5], 0, s[12:13]
	global_store_dwordx2 v[42:43], v[72:73], off
	v_lshl_add_u64 v[46:47], v[44:45], 0, s[12:13]
	v_fma_f32 v72, v72, s10, v34
	v_fma_f32 v73, v73, s10, v35
	global_load_dwordx2 v[34:35], v[46:47], off
	s_add_u32 s12, s12, 0x40000
	s_addc_u32 s13, s13, 0
	s_waitcnt vmcnt(30)
	v_readlane_b32 s10, v8, 45
	v_lshl_add_u64 v[42:43], v[4:5], 0, s[12:13]
	global_store_dwordx2 v[42:43], v[72:73], off
	v_lshl_add_u64 v[46:47], v[44:45], 0, s[12:13]
	v_fma_f32 v72, v72, s10, v36
	v_fma_f32 v73, v73, s10, v37
	global_load_dwordx2 v[36:37], v[46:47], off
	s_add_u32 s12, s12, 0x40000
	s_addc_u32 s13, s13, 0
	s_waitcnt vmcnt(30)
	v_readlane_b32 s10, v8, 46
	v_lshl_add_u64 v[42:43], v[4:5], 0, s[12:13]
	global_store_dwordx2 v[42:43], v[72:73], off
	v_lshl_add_u64 v[46:47], v[44:45], 0, s[12:13]
	v_fma_f32 v72, v72, s10, v38
	v_fma_f32 v73, v73, s10, v39
	global_load_dwordx2 v[38:39], v[46:47], off
	s_add_u32 s12, s12, 0x40000
	s_addc_u32 s13, s13, 0
	s_waitcnt vmcnt(30)
	v_readlane_b32 s10, v8, 47
	v_lshl_add_u64 v[42:43], v[4:5], 0, s[12:13]
	global_store_dwordx2 v[42:43], v[72:73], off
	v_lshl_add_u64 v[46:47], v[44:45], 0, s[12:13]
	v_fma_f32 v72, v72, s10, v40
	v_fma_f32 v73, v73, s10, v41
	global_load_dwordx2 v[40:41], v[46:47], off
	s_add_u32 s12, s12, 0x40000
	s_addc_u32 s13, s13, 0
	s_waitcnt vmcnt(30)
	v_readlane_b32 s10, v8, 48
	v_lshl_add_u64 v[42:43], v[4:5], 0, s[12:13]
	global_store_dwordx2 v[42:43], v[72:73], off
	v_lshl_add_u64 v[46:47], v[44:45], 0, s[12:13]
	v_fma_f32 v72, v72, s10, v10
	v_fma_f32 v73, v73, s10, v11
	global_load_dwordx2 v[10:11], v[46:47], off
	s_add_u32 s12, s12, 0x40000
	s_addc_u32 s13, s13, 0
	s_waitcnt vmcnt(30)
	v_readlane_b32 s10, v8, 49
	v_lshl_add_u64 v[42:43], v[4:5], 0, s[12:13]
	global_store_dwordx2 v[42:43], v[72:73], off
	v_lshl_add_u64 v[46:47], v[44:45], 0, s[12:13]
	v_fma_f32 v72, v72, s10, v12
	v_fma_f32 v73, v73, s10, v13
	global_load_dwordx2 v[12:13], v[46:47], off
	s_add_u32 s12, s12, 0x40000
	s_addc_u32 s13, s13, 0
	s_waitcnt vmcnt(30)
	v_readlane_b32 s10, v8, 50
	v_lshl_add_u64 v[42:43], v[4:5], 0, s[12:13]
	global_store_dwordx2 v[42:43], v[72:73], off
	v_lshl_add_u64 v[46:47], v[44:45], 0, s[12:13]
	v_fma_f32 v72, v72, s10, v14
	v_fma_f32 v73, v73, s10, v15
	global_load_dwordx2 v[14:15], v[46:47], off
	s_add_u32 s12, s12, 0x40000
	s_addc_u32 s13, s13, 0
	s_waitcnt vmcnt(30)
	v_readlane_b32 s10, v8, 51
	v_lshl_add_u64 v[42:43], v[4:5], 0, s[12:13]
	global_store_dwordx2 v[42:43], v[72:73], off
	v_lshl_add_u64 v[46:47], v[44:45], 0, s[12:13]
	v_fma_f32 v72, v72, s10, v16
	v_fma_f32 v73, v73, s10, v17
	global_load_dwordx2 v[16:17], v[46:47], off
	s_add_u32 s12, s12, 0x40000
	s_addc_u32 s13, s13, 0
	s_waitcnt vmcnt(30)
	v_readlane_b32 s10, v8, 52
	v_lshl_add_u64 v[42:43], v[4:5], 0, s[12:13]
	global_store_dwordx2 v[42:43], v[72:73], off
	v_lshl_add_u64 v[46:47], v[44:45], 0, s[12:13]
	v_fma_f32 v72, v72, s10, v18
	v_fma_f32 v73, v73, s10, v19
	global_load_dwordx2 v[18:19], v[46:47], off
	s_add_u32 s12, s12, 0x40000
	s_addc_u32 s13, s13, 0
	s_waitcnt vmcnt(30)
	v_readlane_b32 s10, v8, 53
	v_lshl_add_u64 v[42:43], v[4:5], 0, s[12:13]
	global_store_dwordx2 v[42:43], v[72:73], off
	v_lshl_add_u64 v[46:47], v[44:45], 0, s[12:13]
	v_fma_f32 v72, v72, s10, v20
	v_fma_f32 v73, v73, s10, v21
	global_load_dwordx2 v[20:21], v[46:47], off
	s_add_u32 s12, s12, 0x40000
	s_addc_u32 s13, s13, 0
	s_waitcnt vmcnt(30)
	v_readlane_b32 s10, v8, 54
	v_lshl_add_u64 v[42:43], v[4:5], 0, s[12:13]
	global_store_dwordx2 v[42:43], v[72:73], off
	v_lshl_add_u64 v[46:47], v[44:45], 0, s[12:13]
	v_fma_f32 v72, v72, s10, v22
	v_fma_f32 v73, v73, s10, v23
	global_load_dwordx2 v[22:23], v[46:47], off
	s_add_u32 s12, s12, 0x40000
	s_addc_u32 s13, s13, 0
	s_waitcnt vmcnt(30)
	v_readlane_b32 s10, v8, 55
	v_lshl_add_u64 v[42:43], v[4:5], 0, s[12:13]
	global_store_dwordx2 v[42:43], v[72:73], off
	v_lshl_add_u64 v[46:47], v[44:45], 0, s[12:13]
	v_fma_f32 v72, v72, s10, v24
	v_fma_f32 v73, v73, s10, v25
	global_load_dwordx2 v[24:25], v[46:47], off
	s_add_u32 s12, s12, 0x40000
	s_addc_u32 s13, s13, 0
	s_waitcnt vmcnt(30)
	v_readlane_b32 s10, v8, 56
	v_lshl_add_u64 v[42:43], v[4:5], 0, s[12:13]
	global_store_dwordx2 v[42:43], v[72:73], off
	v_lshl_add_u64 v[46:47], v[44:45], 0, s[12:13]
	v_fma_f32 v72, v72, s10, v26
	v_fma_f32 v73, v73, s10, v27
	global_load_dwordx2 v[26:27], v[46:47], off
	s_add_u32 s12, s12, 0x40000
	s_addc_u32 s13, s13, 0
	s_waitcnt vmcnt(30)
	v_readlane_b32 s10, v8, 57
	v_lshl_add_u64 v[42:43], v[4:5], 0, s[12:13]
	global_store_dwordx2 v[42:43], v[72:73], off
	v_lshl_add_u64 v[46:47], v[44:45], 0, s[12:13]
	v_fma_f32 v72, v72, s10, v28
	v_fma_f32 v73, v73, s10, v29
	global_load_dwordx2 v[28:29], v[46:47], off
	s_add_u32 s12, s12, 0x40000
	s_addc_u32 s13, s13, 0
	s_waitcnt vmcnt(30)
	v_readlane_b32 s10, v8, 58
	v_lshl_add_u64 v[42:43], v[4:5], 0, s[12:13]
	global_store_dwordx2 v[42:43], v[72:73], off
	v_lshl_add_u64 v[46:47], v[44:45], 0, s[12:13]
	v_fma_f32 v72, v72, s10, v30
	v_fma_f32 v73, v73, s10, v31
	global_load_dwordx2 v[30:31], v[46:47], off
	s_add_u32 s12, s12, 0x40000
	s_addc_u32 s13, s13, 0
	s_waitcnt vmcnt(30)
	v_readlane_b32 s10, v8, 59
	v_lshl_add_u64 v[42:43], v[4:5], 0, s[12:13]
	global_store_dwordx2 v[42:43], v[72:73], off
	v_lshl_add_u64 v[46:47], v[44:45], 0, s[12:13]
	v_fma_f32 v72, v72, s10, v32
	v_fma_f32 v73, v73, s10, v33
	global_load_dwordx2 v[32:33], v[46:47], off
	s_add_u32 s12, s12, 0x40000
	s_addc_u32 s13, s13, 0
	s_waitcnt vmcnt(30)
	v_readlane_b32 s10, v8, 60
	v_lshl_add_u64 v[42:43], v[4:5], 0, s[12:13]
	global_store_dwordx2 v[42:43], v[72:73], off
	v_lshl_add_u64 v[46:47], v[44:45], 0, s[12:13]
	v_fma_f32 v72, v72, s10, v34
	v_fma_f32 v73, v73, s10, v35
	global_load_dwordx2 v[34:35], v[46:47], off
	s_add_u32 s12, s12, 0x40000
	s_addc_u32 s13, s13, 0
	s_waitcnt vmcnt(30)
	v_readlane_b32 s10, v8, 61
	v_lshl_add_u64 v[42:43], v[4:5], 0, s[12:13]
	global_store_dwordx2 v[42:43], v[72:73], off
	v_lshl_add_u64 v[46:47], v[44:45], 0, s[12:13]
	v_fma_f32 v72, v72, s10, v36
	v_fma_f32 v73, v73, s10, v37
	global_load_dwordx2 v[36:37], v[46:47], off
	s_add_u32 s12, s12, 0x40000
	s_addc_u32 s13, s13, 0
	s_waitcnt vmcnt(30)
	v_readlane_b32 s10, v8, 62
	v_lshl_add_u64 v[42:43], v[4:5], 0, s[12:13]
	global_store_dwordx2 v[42:43], v[72:73], off
	v_lshl_add_u64 v[46:47], v[44:45], 0, s[12:13]
	v_fma_f32 v72, v72, s10, v38
	v_fma_f32 v73, v73, s10, v39
	global_load_dwordx2 v[38:39], v[46:47], off
	s_add_u32 s12, s12, 0x40000
	s_addc_u32 s13, s13, 0
	s_waitcnt vmcnt(30)
	v_readlane_b32 s10, v8, 63
	v_lshl_add_u64 v[42:43], v[4:5], 0, s[12:13]
	global_store_dwordx2 v[42:43], v[72:73], off
	v_lshl_add_u64 v[46:47], v[44:45], 0, s[12:13]
	v_fma_f32 v72, v72, s10, v40
	v_fma_f32 v73, v73, s10, v41
	global_load_dwordx2 v[40:41], v[46:47], off
	s_add_u32 s12, s12, 0x40000
	s_addc_u32 s13, s13, 0
	s_waitcnt vmcnt(30)
	v_readlane_b32 s10, v9, 0
	v_lshl_add_u64 v[42:43], v[4:5], 0, s[12:13]
	global_store_dwordx2 v[42:43], v[72:73], off
	v_lshl_add_u64 v[46:47], v[44:45], 0, s[12:13]
	v_fma_f32 v72, v72, s10, v10
	v_fma_f32 v73, v73, s10, v11
	global_load_dwordx2 v[10:11], v[46:47], off
	s_add_u32 s12, s12, 0x40000
	s_addc_u32 s13, s13, 0
	s_waitcnt vmcnt(30)
	v_readlane_b32 s10, v9, 1
	v_lshl_add_u64 v[42:43], v[4:5], 0, s[12:13]
	global_store_dwordx2 v[42:43], v[72:73], off
	v_lshl_add_u64 v[46:47], v[44:45], 0, s[12:13]
	v_fma_f32 v72, v72, s10, v12
	v_fma_f32 v73, v73, s10, v13
	global_load_dwordx2 v[12:13], v[46:47], off
	s_add_u32 s12, s12, 0x40000
	s_addc_u32 s13, s13, 0
	s_waitcnt vmcnt(30)
	v_readlane_b32 s10, v9, 2
	v_lshl_add_u64 v[42:43], v[4:5], 0, s[12:13]
	global_store_dwordx2 v[42:43], v[72:73], off
	v_lshl_add_u64 v[46:47], v[44:45], 0, s[12:13]
	v_fma_f32 v72, v72, s10, v14
	v_fma_f32 v73, v73, s10, v15
	global_load_dwordx2 v[14:15], v[46:47], off
	s_add_u32 s12, s12, 0x40000
	s_addc_u32 s13, s13, 0
	s_waitcnt vmcnt(30)
	v_readlane_b32 s10, v9, 3
	v_lshl_add_u64 v[42:43], v[4:5], 0, s[12:13]
	global_store_dwordx2 v[42:43], v[72:73], off
	v_lshl_add_u64 v[46:47], v[44:45], 0, s[12:13]
	v_fma_f32 v72, v72, s10, v16
	v_fma_f32 v73, v73, s10, v17
	global_load_dwordx2 v[16:17], v[46:47], off
	s_add_u32 s12, s12, 0x40000
	s_addc_u32 s13, s13, 0
	s_waitcnt vmcnt(30)
	v_readlane_b32 s10, v9, 4
	v_lshl_add_u64 v[42:43], v[4:5], 0, s[12:13]
	global_store_dwordx2 v[42:43], v[72:73], off
	v_lshl_add_u64 v[46:47], v[44:45], 0, s[12:13]
	v_fma_f32 v72, v72, s10, v18
	v_fma_f32 v73, v73, s10, v19
	global_load_dwordx2 v[18:19], v[46:47], off
	s_add_u32 s12, s12, 0x40000
	s_addc_u32 s13, s13, 0
	s_waitcnt vmcnt(30)
	v_readlane_b32 s10, v9, 5
	v_lshl_add_u64 v[42:43], v[4:5], 0, s[12:13]
	global_store_dwordx2 v[42:43], v[72:73], off
	v_lshl_add_u64 v[46:47], v[44:45], 0, s[12:13]
	v_fma_f32 v72, v72, s10, v20
	v_fma_f32 v73, v73, s10, v21
	global_load_dwordx2 v[20:21], v[46:47], off
	s_add_u32 s12, s12, 0x40000
	s_addc_u32 s13, s13, 0
	s_waitcnt vmcnt(30)
	v_readlane_b32 s10, v9, 6
	v_lshl_add_u64 v[42:43], v[4:5], 0, s[12:13]
	global_store_dwordx2 v[42:43], v[72:73], off
	v_lshl_add_u64 v[46:47], v[44:45], 0, s[12:13]
	v_fma_f32 v72, v72, s10, v22
	v_fma_f32 v73, v73, s10, v23
	global_load_dwordx2 v[22:23], v[46:47], off
	s_add_u32 s12, s12, 0x40000
	s_addc_u32 s13, s13, 0
	s_waitcnt vmcnt(30)
	v_readlane_b32 s10, v9, 7
	v_lshl_add_u64 v[42:43], v[4:5], 0, s[12:13]
	global_store_dwordx2 v[42:43], v[72:73], off
	v_lshl_add_u64 v[46:47], v[44:45], 0, s[12:13]
	v_fma_f32 v72, v72, s10, v24
	v_fma_f32 v73, v73, s10, v25
	global_load_dwordx2 v[24:25], v[46:47], off
	s_add_u32 s12, s12, 0x40000
	s_addc_u32 s13, s13, 0
	s_waitcnt vmcnt(30)
	v_readlane_b32 s10, v9, 8
	v_lshl_add_u64 v[42:43], v[4:5], 0, s[12:13]
	global_store_dwordx2 v[42:43], v[72:73], off
	v_lshl_add_u64 v[46:47], v[44:45], 0, s[12:13]
	v_fma_f32 v72, v72, s10, v26
	v_fma_f32 v73, v73, s10, v27
	global_load_dwordx2 v[26:27], v[46:47], off
	s_add_u32 s12, s12, 0x40000
	s_addc_u32 s13, s13, 0
	s_waitcnt vmcnt(30)
	v_readlane_b32 s10, v9, 9
	v_lshl_add_u64 v[42:43], v[4:5], 0, s[12:13]
	global_store_dwordx2 v[42:43], v[72:73], off
	v_lshl_add_u64 v[46:47], v[44:45], 0, s[12:13]
	v_fma_f32 v72, v72, s10, v28
	v_fma_f32 v73, v73, s10, v29
	global_load_dwordx2 v[28:29], v[46:47], off
	s_add_u32 s12, s12, 0x40000
	s_addc_u32 s13, s13, 0
	s_waitcnt vmcnt(30)
	v_readlane_b32 s10, v9, 10
	v_lshl_add_u64 v[42:43], v[4:5], 0, s[12:13]
	global_store_dwordx2 v[42:43], v[72:73], off
	v_lshl_add_u64 v[46:47], v[44:45], 0, s[12:13]
	v_fma_f32 v72, v72, s10, v30
	v_fma_f32 v73, v73, s10, v31
	global_load_dwordx2 v[30:31], v[46:47], off
	s_add_u32 s12, s12, 0x40000
	s_addc_u32 s13, s13, 0
	s_waitcnt vmcnt(30)
	v_readlane_b32 s10, v9, 11
	v_lshl_add_u64 v[42:43], v[4:5], 0, s[12:13]
	global_store_dwordx2 v[42:43], v[72:73], off
	v_lshl_add_u64 v[46:47], v[44:45], 0, s[12:13]
	v_fma_f32 v72, v72, s10, v32
	v_fma_f32 v73, v73, s10, v33
	global_load_dwordx2 v[32:33], v[46:47], off
	s_add_u32 s12, s12, 0x40000
	s_addc_u32 s13, s13, 0
	s_waitcnt vmcnt(30)
	v_readlane_b32 s10, v9, 12
	v_lshl_add_u64 v[42:43], v[4:5], 0, s[12:13]
	global_store_dwordx2 v[42:43], v[72:73], off
	v_lshl_add_u64 v[46:47], v[44:45], 0, s[12:13]
	v_fma_f32 v72, v72, s10, v34
	v_fma_f32 v73, v73, s10, v35
	global_load_dwordx2 v[34:35], v[46:47], off
	s_add_u32 s12, s12, 0x40000
	s_addc_u32 s13, s13, 0
	s_waitcnt vmcnt(30)
	v_readlane_b32 s10, v9, 13
	v_lshl_add_u64 v[42:43], v[4:5], 0, s[12:13]
	global_store_dwordx2 v[42:43], v[72:73], off
	v_lshl_add_u64 v[46:47], v[44:45], 0, s[12:13]
	v_fma_f32 v72, v72, s10, v36
	v_fma_f32 v73, v73, s10, v37
	global_load_dwordx2 v[36:37], v[46:47], off
	s_add_u32 s12, s12, 0x40000
	s_addc_u32 s13, s13, 0
	s_waitcnt vmcnt(30)
	v_readlane_b32 s10, v9, 14
	v_lshl_add_u64 v[42:43], v[4:5], 0, s[12:13]
	global_store_dwordx2 v[42:43], v[72:73], off
	v_lshl_add_u64 v[46:47], v[44:45], 0, s[12:13]
	v_fma_f32 v72, v72, s10, v38
	v_fma_f32 v73, v73, s10, v39
	global_load_dwordx2 v[38:39], v[46:47], off
	s_add_u32 s12, s12, 0x40000
	s_addc_u32 s13, s13, 0
	s_waitcnt vmcnt(30)
	v_readlane_b32 s10, v9, 15
	v_lshl_add_u64 v[42:43], v[4:5], 0, s[12:13]
	global_store_dwordx2 v[42:43], v[72:73], off
	v_lshl_add_u64 v[46:47], v[44:45], 0, s[12:13]
	v_fma_f32 v72, v72, s10, v40
	v_fma_f32 v73, v73, s10, v41
	global_load_dwordx2 v[40:41], v[46:47], off
	s_add_u32 s12, s12, 0x40000
	s_addc_u32 s13, s13, 0
	s_waitcnt vmcnt(30)
	v_readlane_b32 s10, v9, 16
	v_lshl_add_u64 v[42:43], v[4:5], 0, s[12:13]
	global_store_dwordx2 v[42:43], v[72:73], off
	v_lshl_add_u64 v[46:47], v[44:45], 0, s[12:13]
	v_fma_f32 v72, v72, s10, v10
	v_fma_f32 v73, v73, s10, v11
	global_load_dwordx2 v[10:11], v[46:47], off
	s_add_u32 s12, s12, 0x40000
	s_addc_u32 s13, s13, 0
	s_waitcnt vmcnt(30)
	v_readlane_b32 s10, v9, 17
	v_lshl_add_u64 v[42:43], v[4:5], 0, s[12:13]
	global_store_dwordx2 v[42:43], v[72:73], off
	v_lshl_add_u64 v[46:47], v[44:45], 0, s[12:13]
	v_fma_f32 v72, v72, s10, v12
	v_fma_f32 v73, v73, s10, v13
	global_load_dwordx2 v[12:13], v[46:47], off
	s_add_u32 s12, s12, 0x40000
	s_addc_u32 s13, s13, 0
	s_waitcnt vmcnt(30)
	v_readlane_b32 s10, v9, 18
	v_lshl_add_u64 v[42:43], v[4:5], 0, s[12:13]
	global_store_dwordx2 v[42:43], v[72:73], off
	v_lshl_add_u64 v[46:47], v[44:45], 0, s[12:13]
	v_fma_f32 v72, v72, s10, v14
	v_fma_f32 v73, v73, s10, v15
	global_load_dwordx2 v[14:15], v[46:47], off
	s_add_u32 s12, s12, 0x40000
	s_addc_u32 s13, s13, 0
	s_waitcnt vmcnt(30)
	v_readlane_b32 s10, v9, 19
	v_lshl_add_u64 v[42:43], v[4:5], 0, s[12:13]
	global_store_dwordx2 v[42:43], v[72:73], off
	v_lshl_add_u64 v[46:47], v[44:45], 0, s[12:13]
	v_fma_f32 v72, v72, s10, v16
	v_fma_f32 v73, v73, s10, v17
	global_load_dwordx2 v[16:17], v[46:47], off
	s_add_u32 s12, s12, 0x40000
	s_addc_u32 s13, s13, 0
	s_waitcnt vmcnt(30)
	v_readlane_b32 s10, v9, 20
	v_lshl_add_u64 v[42:43], v[4:5], 0, s[12:13]
	global_store_dwordx2 v[42:43], v[72:73], off
	v_lshl_add_u64 v[46:47], v[44:45], 0, s[12:13]
	v_fma_f32 v72, v72, s10, v18
	v_fma_f32 v73, v73, s10, v19
	global_load_dwordx2 v[18:19], v[46:47], off
	s_add_u32 s12, s12, 0x40000
	s_addc_u32 s13, s13, 0
	s_waitcnt vmcnt(30)
	v_readlane_b32 s10, v9, 21
	v_lshl_add_u64 v[42:43], v[4:5], 0, s[12:13]
	global_store_dwordx2 v[42:43], v[72:73], off
	v_lshl_add_u64 v[46:47], v[44:45], 0, s[12:13]
	v_fma_f32 v72, v72, s10, v20
	v_fma_f32 v73, v73, s10, v21
	global_load_dwordx2 v[20:21], v[46:47], off
	s_add_u32 s12, s12, 0x40000
	s_addc_u32 s13, s13, 0
	s_waitcnt vmcnt(30)
	v_readlane_b32 s10, v9, 22
	v_lshl_add_u64 v[42:43], v[4:5], 0, s[12:13]
	global_store_dwordx2 v[42:43], v[72:73], off
	v_lshl_add_u64 v[46:47], v[44:45], 0, s[12:13]
	v_fma_f32 v72, v72, s10, v22
	v_fma_f32 v73, v73, s10, v23
	global_load_dwordx2 v[22:23], v[46:47], off
	s_add_u32 s12, s12, 0x40000
	s_addc_u32 s13, s13, 0
	s_waitcnt vmcnt(30)
	v_readlane_b32 s10, v9, 23
	v_lshl_add_u64 v[42:43], v[4:5], 0, s[12:13]
	global_store_dwordx2 v[42:43], v[72:73], off
	v_lshl_add_u64 v[46:47], v[44:45], 0, s[12:13]
	v_fma_f32 v72, v72, s10, v24
	v_fma_f32 v73, v73, s10, v25
	global_load_dwordx2 v[24:25], v[46:47], off
	s_add_u32 s12, s12, 0x40000
	s_addc_u32 s13, s13, 0
	s_waitcnt vmcnt(30)
	v_readlane_b32 s10, v9, 24
	v_lshl_add_u64 v[42:43], v[4:5], 0, s[12:13]
	global_store_dwordx2 v[42:43], v[72:73], off
	v_lshl_add_u64 v[46:47], v[44:45], 0, s[12:13]
	v_fma_f32 v72, v72, s10, v26
	v_fma_f32 v73, v73, s10, v27
	global_load_dwordx2 v[26:27], v[46:47], off
	s_add_u32 s12, s12, 0x40000
	s_addc_u32 s13, s13, 0
	s_waitcnt vmcnt(30)
	v_readlane_b32 s10, v9, 25
	v_lshl_add_u64 v[42:43], v[4:5], 0, s[12:13]
	global_store_dwordx2 v[42:43], v[72:73], off
	v_lshl_add_u64 v[46:47], v[44:45], 0, s[12:13]
	v_fma_f32 v72, v72, s10, v28
	v_fma_f32 v73, v73, s10, v29
	global_load_dwordx2 v[28:29], v[46:47], off
	s_add_u32 s12, s12, 0x40000
	s_addc_u32 s13, s13, 0
	s_waitcnt vmcnt(30)
	v_readlane_b32 s10, v9, 26
	v_lshl_add_u64 v[42:43], v[4:5], 0, s[12:13]
	global_store_dwordx2 v[42:43], v[72:73], off
	v_lshl_add_u64 v[46:47], v[44:45], 0, s[12:13]
	v_fma_f32 v72, v72, s10, v30
	v_fma_f32 v73, v73, s10, v31
	global_load_dwordx2 v[30:31], v[46:47], off
	s_add_u32 s12, s12, 0x40000
	s_addc_u32 s13, s13, 0
	s_waitcnt vmcnt(30)
	v_readlane_b32 s10, v9, 27
	v_lshl_add_u64 v[42:43], v[4:5], 0, s[12:13]
	global_store_dwordx2 v[42:43], v[72:73], off
	v_lshl_add_u64 v[46:47], v[44:45], 0, s[12:13]
	v_fma_f32 v72, v72, s10, v32
	v_fma_f32 v73, v73, s10, v33
	global_load_dwordx2 v[32:33], v[46:47], off
	s_add_u32 s12, s12, 0x40000
	s_addc_u32 s13, s13, 0
	s_waitcnt vmcnt(30)
	v_readlane_b32 s10, v9, 28
	v_lshl_add_u64 v[42:43], v[4:5], 0, s[12:13]
	global_store_dwordx2 v[42:43], v[72:73], off
	v_lshl_add_u64 v[46:47], v[44:45], 0, s[12:13]
	v_fma_f32 v72, v72, s10, v34
	v_fma_f32 v73, v73, s10, v35
	global_load_dwordx2 v[34:35], v[46:47], off
	s_add_u32 s12, s12, 0x40000
	s_addc_u32 s13, s13, 0
	s_waitcnt vmcnt(30)
	v_readlane_b32 s10, v9, 29
	v_lshl_add_u64 v[42:43], v[4:5], 0, s[12:13]
	global_store_dwordx2 v[42:43], v[72:73], off
	v_lshl_add_u64 v[46:47], v[44:45], 0, s[12:13]
	v_fma_f32 v72, v72, s10, v36
	v_fma_f32 v73, v73, s10, v37
	global_load_dwordx2 v[36:37], v[46:47], off
	s_add_u32 s12, s12, 0x40000
	s_addc_u32 s13, s13, 0
	s_waitcnt vmcnt(30)
	v_readlane_b32 s10, v9, 30
	v_lshl_add_u64 v[42:43], v[4:5], 0, s[12:13]
	global_store_dwordx2 v[42:43], v[72:73], off
	v_lshl_add_u64 v[46:47], v[44:45], 0, s[12:13]
	v_fma_f32 v72, v72, s10, v38
	v_fma_f32 v73, v73, s10, v39
	global_load_dwordx2 v[38:39], v[46:47], off
	s_add_u32 s12, s12, 0x40000
	s_addc_u32 s13, s13, 0
	s_waitcnt vmcnt(30)
	v_readlane_b32 s10, v9, 31
	v_lshl_add_u64 v[42:43], v[4:5], 0, s[12:13]
	global_store_dwordx2 v[42:43], v[72:73], off
	v_lshl_add_u64 v[46:47], v[44:45], 0, s[12:13]
	v_fma_f32 v72, v72, s10, v40
	v_fma_f32 v73, v73, s10, v41
	global_load_dwordx2 v[40:41], v[46:47], off
	s_add_u32 s12, s12, 0x40000
	s_addc_u32 s13, s13, 0
	s_waitcnt vmcnt(30)
	v_readlane_b32 s10, v9, 32
	v_lshl_add_u64 v[42:43], v[4:5], 0, s[12:13]
	global_store_dwordx2 v[42:43], v[72:73], off
	v_lshl_add_u64 v[46:47], v[44:45], 0, s[12:13]
	v_fma_f32 v72, v72, s10, v10
	v_fma_f32 v73, v73, s10, v11
	global_load_dwordx2 v[10:11], v[46:47], off
	s_add_u32 s12, s12, 0x40000
	s_addc_u32 s13, s13, 0
	s_waitcnt vmcnt(30)
	v_readlane_b32 s10, v9, 33
	v_lshl_add_u64 v[42:43], v[4:5], 0, s[12:13]
	global_store_dwordx2 v[42:43], v[72:73], off
	v_lshl_add_u64 v[46:47], v[44:45], 0, s[12:13]
	v_fma_f32 v72, v72, s10, v12
	v_fma_f32 v73, v73, s10, v13
	global_load_dwordx2 v[12:13], v[46:47], off
	s_add_u32 s12, s12, 0x40000
	s_addc_u32 s13, s13, 0
	s_waitcnt vmcnt(30)
	v_readlane_b32 s10, v9, 34
	v_lshl_add_u64 v[42:43], v[4:5], 0, s[12:13]
	global_store_dwordx2 v[42:43], v[72:73], off
	v_lshl_add_u64 v[46:47], v[44:45], 0, s[12:13]
	v_fma_f32 v72, v72, s10, v14
	v_fma_f32 v73, v73, s10, v15
	global_load_dwordx2 v[14:15], v[46:47], off
	s_add_u32 s12, s12, 0x40000
	s_addc_u32 s13, s13, 0
	s_waitcnt vmcnt(30)
	v_readlane_b32 s10, v9, 35
	v_lshl_add_u64 v[42:43], v[4:5], 0, s[12:13]
	global_store_dwordx2 v[42:43], v[72:73], off
	v_lshl_add_u64 v[46:47], v[44:45], 0, s[12:13]
	v_fma_f32 v72, v72, s10, v16
	v_fma_f32 v73, v73, s10, v17
	global_load_dwordx2 v[16:17], v[46:47], off
	s_add_u32 s12, s12, 0x40000
	s_addc_u32 s13, s13, 0
	s_waitcnt vmcnt(30)
	v_readlane_b32 s10, v9, 36
	v_lshl_add_u64 v[42:43], v[4:5], 0, s[12:13]
	global_store_dwordx2 v[42:43], v[72:73], off
	v_lshl_add_u64 v[46:47], v[44:45], 0, s[12:13]
	v_fma_f32 v72, v72, s10, v18
	v_fma_f32 v73, v73, s10, v19
	global_load_dwordx2 v[18:19], v[46:47], off
	s_add_u32 s12, s12, 0x40000
	s_addc_u32 s13, s13, 0
	s_waitcnt vmcnt(30)
	v_readlane_b32 s10, v9, 37
	v_lshl_add_u64 v[42:43], v[4:5], 0, s[12:13]
	global_store_dwordx2 v[42:43], v[72:73], off
	v_lshl_add_u64 v[46:47], v[44:45], 0, s[12:13]
	v_fma_f32 v72, v72, s10, v20
	v_fma_f32 v73, v73, s10, v21
	global_load_dwordx2 v[20:21], v[46:47], off
	s_add_u32 s12, s12, 0x40000
	s_addc_u32 s13, s13, 0
	s_waitcnt vmcnt(30)
	v_readlane_b32 s10, v9, 38
	v_lshl_add_u64 v[42:43], v[4:5], 0, s[12:13]
	global_store_dwordx2 v[42:43], v[72:73], off
	v_lshl_add_u64 v[46:47], v[44:45], 0, s[12:13]
	v_fma_f32 v72, v72, s10, v22
	v_fma_f32 v73, v73, s10, v23
	global_load_dwordx2 v[22:23], v[46:47], off
	s_add_u32 s12, s12, 0x40000
	s_addc_u32 s13, s13, 0
	s_waitcnt vmcnt(30)
	v_readlane_b32 s10, v9, 39
	v_lshl_add_u64 v[42:43], v[4:5], 0, s[12:13]
	global_store_dwordx2 v[42:43], v[72:73], off
	v_lshl_add_u64 v[46:47], v[44:45], 0, s[12:13]
	v_fma_f32 v72, v72, s10, v24
	v_fma_f32 v73, v73, s10, v25
	global_load_dwordx2 v[24:25], v[46:47], off
	s_add_u32 s12, s12, 0x40000
	s_addc_u32 s13, s13, 0
	s_waitcnt vmcnt(30)
	v_readlane_b32 s10, v9, 40
	v_lshl_add_u64 v[42:43], v[4:5], 0, s[12:13]
	global_store_dwordx2 v[42:43], v[72:73], off
	v_lshl_add_u64 v[46:47], v[44:45], 0, s[12:13]
	v_fma_f32 v72, v72, s10, v26
	v_fma_f32 v73, v73, s10, v27
	global_load_dwordx2 v[26:27], v[46:47], off
	s_add_u32 s12, s12, 0x40000
	s_addc_u32 s13, s13, 0
	s_waitcnt vmcnt(30)
	v_readlane_b32 s10, v9, 41
	v_lshl_add_u64 v[42:43], v[4:5], 0, s[12:13]
	global_store_dwordx2 v[42:43], v[72:73], off
	v_lshl_add_u64 v[46:47], v[44:45], 0, s[12:13]
	v_fma_f32 v72, v72, s10, v28
	v_fma_f32 v73, v73, s10, v29
	global_load_dwordx2 v[28:29], v[46:47], off
	s_add_u32 s12, s12, 0x40000
	s_addc_u32 s13, s13, 0
	s_waitcnt vmcnt(30)
	v_readlane_b32 s10, v9, 42
	v_lshl_add_u64 v[42:43], v[4:5], 0, s[12:13]
	global_store_dwordx2 v[42:43], v[72:73], off
	v_lshl_add_u64 v[46:47], v[44:45], 0, s[12:13]
	v_fma_f32 v72, v72, s10, v30
	v_fma_f32 v73, v73, s10, v31
	global_load_dwordx2 v[30:31], v[46:47], off
	s_add_u32 s12, s12, 0x40000
	s_addc_u32 s13, s13, 0
	s_waitcnt vmcnt(30)
	v_readlane_b32 s10, v9, 43
	v_lshl_add_u64 v[42:43], v[4:5], 0, s[12:13]
	global_store_dwordx2 v[42:43], v[72:73], off
	v_lshl_add_u64 v[46:47], v[44:45], 0, s[12:13]
	v_fma_f32 v72, v72, s10, v32
	v_fma_f32 v73, v73, s10, v33
	global_load_dwordx2 v[32:33], v[46:47], off
	s_add_u32 s12, s12, 0x40000
	s_addc_u32 s13, s13, 0
	s_waitcnt vmcnt(30)
	v_readlane_b32 s10, v9, 44
	v_lshl_add_u64 v[42:43], v[4:5], 0, s[12:13]
	global_store_dwordx2 v[42:43], v[72:73], off
	v_lshl_add_u64 v[46:47], v[44:45], 0, s[12:13]
	v_fma_f32 v72, v72, s10, v34
	v_fma_f32 v73, v73, s10, v35
	global_load_dwordx2 v[34:35], v[46:47], off
	s_add_u32 s12, s12, 0x40000
	s_addc_u32 s13, s13, 0
	s_waitcnt vmcnt(30)
	v_readlane_b32 s10, v9, 45
	v_lshl_add_u64 v[42:43], v[4:5], 0, s[12:13]
	global_store_dwordx2 v[42:43], v[72:73], off
	v_lshl_add_u64 v[46:47], v[44:45], 0, s[12:13]
	v_fma_f32 v72, v72, s10, v36
	v_fma_f32 v73, v73, s10, v37
	global_load_dwordx2 v[36:37], v[46:47], off
	s_add_u32 s12, s12, 0x40000
	s_addc_u32 s13, s13, 0
	s_waitcnt vmcnt(30)
	v_readlane_b32 s10, v9, 46
	v_lshl_add_u64 v[42:43], v[4:5], 0, s[12:13]
	global_store_dwordx2 v[42:43], v[72:73], off
	v_lshl_add_u64 v[46:47], v[44:45], 0, s[12:13]
	v_fma_f32 v72, v72, s10, v38
	v_fma_f32 v73, v73, s10, v39
	global_load_dwordx2 v[38:39], v[46:47], off
	s_add_u32 s12, s12, 0x40000
	s_addc_u32 s13, s13, 0
	s_waitcnt vmcnt(30)
	v_readlane_b32 s10, v9, 47
	v_lshl_add_u64 v[42:43], v[4:5], 0, s[12:13]
	global_store_dwordx2 v[42:43], v[72:73], off
	v_lshl_add_u64 v[46:47], v[44:45], 0, s[12:13]
	v_fma_f32 v72, v72, s10, v40
	v_fma_f32 v73, v73, s10, v41
	global_load_dwordx2 v[40:41], v[46:47], off
	s_add_u32 s12, s12, 0x40000
	s_addc_u32 s13, s13, 0
	s_waitcnt vmcnt(30)
	v_readlane_b32 s10, v9, 48
	v_lshl_add_u64 v[42:43], v[4:5], 0, s[12:13]
	global_store_dwordx2 v[42:43], v[72:73], off
	v_fma_f32 v72, v72, s10, v10
	v_fma_f32 v73, v73, s10, v11
	s_add_u32 s12, s12, 0x40000
	s_addc_u32 s13, s13, 0
	s_waitcnt vmcnt(29)
	v_readlane_b32 s10, v9, 49
	v_lshl_add_u64 v[42:43], v[4:5], 0, s[12:13]
	global_store_dwordx2 v[42:43], v[72:73], off
	v_fma_f32 v72, v72, s10, v12
	v_fma_f32 v73, v73, s10, v13
	s_add_u32 s12, s12, 0x40000
	s_addc_u32 s13, s13, 0
	s_waitcnt vmcnt(28)
	v_readlane_b32 s10, v9, 50
	v_lshl_add_u64 v[42:43], v[4:5], 0, s[12:13]
	global_store_dwordx2 v[42:43], v[72:73], off
	v_fma_f32 v72, v72, s10, v14
	v_fma_f32 v73, v73, s10, v15
	s_add_u32 s12, s12, 0x40000
	s_addc_u32 s13, s13, 0
	s_waitcnt vmcnt(27)
	v_readlane_b32 s10, v9, 51
	v_lshl_add_u64 v[42:43], v[4:5], 0, s[12:13]
	global_store_dwordx2 v[42:43], v[72:73], off
	v_fma_f32 v72, v72, s10, v16
	v_fma_f32 v73, v73, s10, v17
	s_add_u32 s12, s12, 0x40000
	s_addc_u32 s13, s13, 0
	s_waitcnt vmcnt(26)
	v_readlane_b32 s10, v9, 52
	v_lshl_add_u64 v[42:43], v[4:5], 0, s[12:13]
	global_store_dwordx2 v[42:43], v[72:73], off
	v_fma_f32 v72, v72, s10, v18
	v_fma_f32 v73, v73, s10, v19
	s_add_u32 s12, s12, 0x40000
	s_addc_u32 s13, s13, 0
	s_waitcnt vmcnt(25)
	v_readlane_b32 s10, v9, 53
	v_lshl_add_u64 v[42:43], v[4:5], 0, s[12:13]
	global_store_dwordx2 v[42:43], v[72:73], off
	v_fma_f32 v72, v72, s10, v20
	v_fma_f32 v73, v73, s10, v21
	s_add_u32 s12, s12, 0x40000
	s_addc_u32 s13, s13, 0
	s_waitcnt vmcnt(24)
	v_readlane_b32 s10, v9, 54
	v_lshl_add_u64 v[42:43], v[4:5], 0, s[12:13]
	global_store_dwordx2 v[42:43], v[72:73], off
	v_fma_f32 v72, v72, s10, v22
	v_fma_f32 v73, v73, s10, v23
	s_add_u32 s12, s12, 0x40000
	s_addc_u32 s13, s13, 0
	s_waitcnt vmcnt(23)
	v_readlane_b32 s10, v9, 55
	v_lshl_add_u64 v[42:43], v[4:5], 0, s[12:13]
	global_store_dwordx2 v[42:43], v[72:73], off
	v_fma_f32 v72, v72, s10, v24
	v_fma_f32 v73, v73, s10, v25
	s_add_u32 s12, s12, 0x40000
	s_addc_u32 s13, s13, 0
	s_waitcnt vmcnt(22)
	v_readlane_b32 s10, v9, 56
	v_lshl_add_u64 v[42:43], v[4:5], 0, s[12:13]
	global_store_dwordx2 v[42:43], v[72:73], off
	v_fma_f32 v72, v72, s10, v26
	v_fma_f32 v73, v73, s10, v27
	s_add_u32 s12, s12, 0x40000
	s_addc_u32 s13, s13, 0
	s_waitcnt vmcnt(21)
	v_readlane_b32 s10, v9, 57
	v_lshl_add_u64 v[42:43], v[4:5], 0, s[12:13]
	global_store_dwordx2 v[42:43], v[72:73], off
	v_fma_f32 v72, v72, s10, v28
	v_fma_f32 v73, v73, s10, v29
	s_add_u32 s12, s12, 0x40000
	s_addc_u32 s13, s13, 0
	s_waitcnt vmcnt(20)
	v_readlane_b32 s10, v9, 58
	v_lshl_add_u64 v[42:43], v[4:5], 0, s[12:13]
	global_store_dwordx2 v[42:43], v[72:73], off
	v_fma_f32 v72, v72, s10, v30
	v_fma_f32 v73, v73, s10, v31
	s_add_u32 s12, s12, 0x40000
	s_addc_u32 s13, s13, 0
	s_waitcnt vmcnt(19)
	v_readlane_b32 s10, v9, 59
	v_lshl_add_u64 v[42:43], v[4:5], 0, s[12:13]
	global_store_dwordx2 v[42:43], v[72:73], off
	v_fma_f32 v72, v72, s10, v32
	v_fma_f32 v73, v73, s10, v33
	s_add_u32 s12, s12, 0x40000
	s_addc_u32 s13, s13, 0
	s_waitcnt vmcnt(18)
	v_readlane_b32 s10, v9, 60
	v_lshl_add_u64 v[42:43], v[4:5], 0, s[12:13]
	global_store_dwordx2 v[42:43], v[72:73], off
	v_fma_f32 v72, v72, s10, v34
	v_fma_f32 v73, v73, s10, v35
	s_add_u32 s12, s12, 0x40000
	s_addc_u32 s13, s13, 0
	s_waitcnt vmcnt(17)
	v_readlane_b32 s10, v9, 61
	v_lshl_add_u64 v[42:43], v[4:5], 0, s[12:13]
	global_store_dwordx2 v[42:43], v[72:73], off
	v_fma_f32 v72, v72, s10, v36
	v_fma_f32 v73, v73, s10, v37
	s_add_u32 s12, s12, 0x40000
	s_addc_u32 s13, s13, 0
	s_waitcnt vmcnt(16)
	v_readlane_b32 s10, v9, 62
	v_lshl_add_u64 v[42:43], v[4:5], 0, s[12:13]
	global_store_dwordx2 v[42:43], v[72:73], off
	v_fma_f32 v72, v72, s10, v38
	v_fma_f32 v73, v73, s10, v39
	s_add_u32 s12, s12, 0x40000
	s_addc_u32 s13, s13, 0
	s_waitcnt vmcnt(15)
	v_readlane_b32 s10, v9, 63
	v_lshl_add_u64 v[42:43], v[4:5], 0, s[12:13]
	global_store_dwordx2 v[42:43], v[72:73], off
	v_fma_f32 v72, v72, s10, v40
	v_fma_f32 v73, v73, s10, v41
	s_add_u32 s12, s12, 0x40000
	s_addc_u32 s13, s13, 0
	v_lshlrev_b32_e32 v4, 1, v74
	v_add_u32_e32 v74, s4, v74
	v_ashrrev_i32_e32 v5, 31, v4
	v_cmp_lt_i32_e32 vcc, s14, v74
	v_lshl_add_u64 v[4:5], v[4:5], 2, s[6:7]
	s_or_b64 s[8:9], vcc, s[8:9]
	v_add_u32_e32 v75, s5, v75
	global_store_dwordx2 v[4:5], v[72:73], off
	s_andn2_b64 exec, exec, s[8:9]
	s_cbranch_execnz .LBB0_1888
